# EpiResid epilogues (P3,P6,P8) rewritten by hand: batched cross-lane reductions (2 LDS round trips instead of 16), 497 vs 669 instr per wave
# speedup vs baseline: 1.0074x; 1.0074x over previous
; __device__ __forceinline__ unsigned cvt_pk_bf16(float lo, float hi) { unsigned r; asm volatile("v_cvt_pk_bf16_f32 %0, %1, %2" : "=v"(r) : "v"(lo), "v"(hi)); return r; }
;     __device__ __forceinline__ void operator()(const f32x4 (&acc)[2][2][4][2], const Unit& u, int wr, int wc, int fr, int fq) const {
;         const int row0 = u.pm * BM + wr * 64 + fr, col0 = u.pn * BM + wc * 32 + 8 * fq;
;         u32x4 bw[2][4][2];
; #pragma unroll
;         for (int ai = 0; ai < 2; ++ai)
; #pragma unroll
;             for (int m = 0; m < 4; ++m)
; #pragma unroll
;                 for (int bj = 0; bj < 2; ++bj) bw[ai][m][bj] = *(const u32x4*)(hb + (size_t)(row0 + ai * HALF + m * 16) * 1024 + col0 + bj * HALF);
; #pragma unroll
;         for (int ai = 0; ai < 2; ++ai) {
; #pragma unroll
;             for (int m = 0; m < 4; ++m) { const int row = row0 + ai * HALF + m * 16; const size_t off = (size_t)row * 1024 + col0; float ss = 0.f;
; #pragma unroll
;                 for (int bj = 0; bj < 2; ++bj) {
;                     const u32x4 b = bw[ai][m][bj];
;                     const f32x4 b0 = (f32x4){__uint_as_float(b.x << 16), __uint_as_float(b.x & 0xffff0000u), __uint_as_float(b.y << 16), __uint_as_float(b.y & 0xffff0000u)};
;                     const f32x4 b1 = (f32x4){__uint_as_float(b.z << 16), __uint_as_float(b.z & 0xffff0000u), __uint_as_float(b.w << 16), __uint_as_float(b.w & 0xffff0000u)};
;                     const f32x4 v0 = acc[ai][bj][m][0] + b0, v1 = acc[ai][bj][m][1] + b1;
;                     ss += (v0[0] * v0[0] + v0[1] * v0[1]) + (v0[2] * v0[2] + v0[3] * v0[3]) + (v1[0] * v1[0] + v1[1] * v1[1]) + (v1[2] * v1[2] + v1[3] * v1[3]);
;                     u32x4 w; w.x = cvt_pk_bf16(v0[0], v0[1]); w.y = cvt_pk_bf16(v0[2], v0[3]); w.z = cvt_pk_bf16(v1[0], v1[1]); w.w = cvt_pk_bf16(v1[2], v1[3]);
;                     *(u32x4*)(hb + off + bj * HALF) = w; }
;                 ss += __shfl_xor(ss, 16); ss += __shfl_xor(ss, 32);
;                 if (fq == 0) slots[(size_t)row * 16 + u.pn * 4 + wc] = ss; }
;             asm volatile("" ::: "memory");
;         }
;     }
.LBB0_593:
	v_lshl_add_u32 v228, s67, 8, v248
	v_lshl_or_b32 v229, s6, 8, v250
	s_lshl_b32 s24, s6, 4
	s_lshl_b32 s86, s61, 2
	v_lshlrev_b32_e32 v240, 6, v228
	v_lshlrev_b32_e32 v228, 11, v228
	s_add_i32 s24, s24, s86
	v_lshl_add_u32 v228, v229, 1, v228
	v_add_u32_e32 v240, s24, v240
	global_load_dwordx4 v[112:115], v228, s[4:5]
	global_load_dwordx4 v[120:123], v228, s[4:5] offset:256
	v_add_u32_e32 v229, 0x8000, v228
	global_load_dwordx4 v[124:127], v229, s[4:5]
	global_load_dwordx4 v[128:131], v229, s[4:5] offset:256
	v_add_u32_e32 v229, 0x10000, v228
	global_load_dwordx4 v[136:139], v229, s[4:5]
	global_load_dwordx4 v[140:143], v229, s[4:5] offset:256
	v_add_u32_e32 v229, 0x18000, v228
	global_load_dwordx4 v[144:147], v229, s[4:5]
	global_load_dwordx4 v[156:159], v229, s[4:5] offset:256
	v_add_u32_e32 v229, 0x40000, v228
	global_load_dwordx4 v[160:163], v229, s[4:5]
	global_load_dwordx4 v[164:167], v229, s[4:5] offset:256
	v_add_u32_e32 v229, 0x48000, v228
	global_load_dwordx4 v[168:171], v229, s[4:5]
	global_load_dwordx4 v[172:175], v229, s[4:5] offset:256
	v_add_u32_e32 v229, 0x50000, v228
	global_load_dwordx4 v[176:179], v229, s[4:5]
	global_load_dwordx4 v[180:183], v229, s[4:5] offset:256
	v_add_u32_e32 v229, 0x58000, v228
	global_load_dwordx4 v[184:187], v229, s[4:5]
	global_load_dwordx4 v[188:191], v229, s[4:5] offset:256
	v_xor_b32_e32 v230, 16, v252
	v_xor_b32_e32 v231, 32, v252
	v_add_u32_e32 v241, 0x2000, v240
	v_lshlrev_b32_e32 v230, 2, v230
	v_lshlrev_b32_e32 v231, 2, v231
	s_waitcnt vmcnt(0)
	v_lshlrev_b32_e32 v194, 16, v112
	v_and_b32_e32 v195, 0xffff0000, v112
	v_lshlrev_b32_e32 v196, 16, v113
	v_and_b32_e32 v197, 0xffff0000, v113
	v_lshlrev_b32_e32 v208, 16, v114
	v_and_b32_e32 v209, 0xffff0000, v114
	v_lshlrev_b32_e32 v210, 16, v115
	v_and_b32_e32 v211, 0xffff0000, v115
	v_pk_add_f32 v[152:153], v[152:153], v[194:195]
	v_pk_add_f32 v[154:155], v[154:155], v[196:197]
	v_pk_add_f32 v[148:149], v[148:149], v[208:209]
	v_pk_add_f32 v[150:151], v[150:151], v[210:211]
	v_mul_f32_e32 v212, v152, v152
	v_fmac_f32_e32 v212, v153, v153
	v_fmac_f32_e32 v212, v154, v154
	v_fmac_f32_e32 v212, v155, v155
	v_fmac_f32_e32 v212, v148, v148
	v_fmac_f32_e32 v212, v149, v149
	v_fmac_f32_e32 v212, v150, v150
	v_fmac_f32_e32 v212, v151, v151
	v_cvt_pk_bf16_f32 v112, v152, v153
	v_cvt_pk_bf16_f32 v113, v154, v155
	v_cvt_pk_bf16_f32 v114, v148, v149
	v_cvt_pk_bf16_f32 v115, v150, v151
	global_store_dwordx4 v228, v[112:115], s[4:5]
	v_lshlrev_b32_e32 v194, 16, v120
	v_and_b32_e32 v195, 0xffff0000, v120
	v_lshlrev_b32_e32 v196, 16, v121
	v_and_b32_e32 v197, 0xffff0000, v121
	v_lshlrev_b32_e32 v208, 16, v122
	v_and_b32_e32 v209, 0xffff0000, v122
	v_lshlrev_b32_e32 v210, 16, v123
	v_and_b32_e32 v211, 0xffff0000, v123
	v_pk_add_f32 v[132:133], v[132:133], v[194:195]
	v_pk_add_f32 v[134:135], v[134:135], v[196:197]
	v_pk_add_f32 v[116:117], v[116:117], v[208:209]
	v_pk_add_f32 v[118:119], v[118:119], v[210:211]
	v_mul_f32_e32 v220, v132, v132
	v_fmac_f32_e32 v220, v133, v133
	v_fmac_f32_e32 v220, v134, v134
	v_fmac_f32_e32 v220, v135, v135
	v_fmac_f32_e32 v220, v116, v116
	v_fmac_f32_e32 v220, v117, v117
	v_fmac_f32_e32 v220, v118, v118
	v_fmac_f32_e32 v220, v119, v119
	v_cvt_pk_bf16_f32 v120, v132, v133
	v_cvt_pk_bf16_f32 v121, v134, v135
	v_cvt_pk_bf16_f32 v122, v116, v117
	v_cvt_pk_bf16_f32 v123, v118, v119
	global_store_dwordx4 v228, v[120:123], s[4:5] offset:256
	v_add_u32_e32 v229, 0x8000, v228
	v_lshlrev_b32_e32 v194, 16, v124
	v_and_b32_e32 v195, 0xffff0000, v124
	v_lshlrev_b32_e32 v196, 16, v125
	v_and_b32_e32 v197, 0xffff0000, v125
	v_lshlrev_b32_e32 v208, 16, v126
	v_and_b32_e32 v209, 0xffff0000, v126
	v_lshlrev_b32_e32 v210, 16, v127
	v_and_b32_e32 v211, 0xffff0000, v127
	v_pk_add_f32 v[108:109], v[108:109], v[194:195]
	v_pk_add_f32 v[110:111], v[110:111], v[196:197]
	v_pk_add_f32 v[104:105], v[104:105], v[208:209]
	v_pk_add_f32 v[106:107], v[106:107], v[210:211]
	v_mul_f32_e32 v213, v108, v108
	v_fmac_f32_e32 v213, v109, v109
	v_fmac_f32_e32 v213, v110, v110
	v_fmac_f32_e32 v213, v111, v111
	v_fmac_f32_e32 v213, v104, v104
	v_fmac_f32_e32 v213, v105, v105
	v_fmac_f32_e32 v213, v106, v106
	v_fmac_f32_e32 v213, v107, v107
	v_cvt_pk_bf16_f32 v124, v108, v109
	v_cvt_pk_bf16_f32 v125, v110, v111
	v_cvt_pk_bf16_f32 v126, v104, v105
	v_cvt_pk_bf16_f32 v127, v106, v107
	global_store_dwordx4 v229, v[124:127], s[4:5]
	v_lshlrev_b32_e32 v194, 16, v128
	v_and_b32_e32 v195, 0xffff0000, v128
	v_lshlrev_b32_e32 v196, 16, v129
	v_and_b32_e32 v197, 0xffff0000, v129
	v_lshlrev_b32_e32 v208, 16, v130
	v_and_b32_e32 v209, 0xffff0000, v130
	v_lshlrev_b32_e32 v210, 16, v131
	v_and_b32_e32 v211, 0xffff0000, v131
	v_pk_add_f32 v[100:101], v[100:101], v[194:195]
	v_pk_add_f32 v[102:103], v[102:103], v[196:197]
	v_pk_add_f32 v[96:97], v[96:97], v[208:209]
	v_pk_add_f32 v[98:99], v[98:99], v[210:211]
	v_mul_f32_e32 v221, v100, v100
	v_fmac_f32_e32 v221, v101, v101
	v_fmac_f32_e32 v221, v102, v102
	v_fmac_f32_e32 v221, v103, v103
	v_fmac_f32_e32 v221, v96, v96
	v_fmac_f32_e32 v221, v97, v97
	v_fmac_f32_e32 v221, v98, v98
	v_fmac_f32_e32 v221, v99, v99
	v_cvt_pk_bf16_f32 v128, v100, v101
	v_cvt_pk_bf16_f32 v129, v102, v103
	v_cvt_pk_bf16_f32 v130, v96, v97
	v_cvt_pk_bf16_f32 v131, v98, v99
	global_store_dwordx4 v229, v[128:131], s[4:5] offset:256
	v_add_u32_e32 v229, 0x10000, v228
	v_lshlrev_b32_e32 v194, 16, v136
	v_and_b32_e32 v195, 0xffff0000, v136
	v_lshlrev_b32_e32 v196, 16, v137
	v_and_b32_e32 v197, 0xffff0000, v137
	v_lshlrev_b32_e32 v208, 16, v138
	v_and_b32_e32 v209, 0xffff0000, v138
	v_lshlrev_b32_e32 v210, 16, v139
	v_and_b32_e32 v211, 0xffff0000, v139
; __device__ __forceinline__ unsigned cvt_pk_bf16(float lo, float hi) { unsigned r; asm volatile("v_cvt_pk_bf16_f32 %0, %1, %2" : "=v"(r) : "v"(lo), "v"(hi)); return r; }
;     __device__ __forceinline__ void operator()(const f32x4 (&acc)[2][2][4][2], const Unit& u, int wr, int wc, int fr, int fq) const {
;     ...
;             for (int m = 0; m < 4; ++m) { const int row = row0 + ai * HALF + m * 16; const size_t off = (size_t)row * 1024 + col0; float ss = 0.f;
; #pragma unroll
;                 for (int bj = 0; bj < 2; ++bj) {
;                     const u32x4 b = bw[ai][m][bj];
;                     const f32x4 b0 = (f32x4){__uint_as_float(b.x << 16), __uint_as_float(b.x & 0xffff0000u), __uint_as_float(b.y << 16), __uint_as_float(b.y & 0xffff0000u)};
;                     const f32x4 b1 = (f32x4){__uint_as_float(b.z << 16), __uint_as_float(b.z & 0xffff0000u), __uint_as_float(b.w << 16), __uint_as_float(b.w & 0xffff0000u)};
;                     const f32x4 v0 = acc[ai][bj][m][0] + b0, v1 = acc[ai][bj][m][1] + b1;
;                     ss += (v0[0] * v0[0] + v0[1] * v0[1]) + (v0[2] * v0[2] + v0[3] * v0[3]) + (v1[0] * v1[0] + v1[1] * v1[1]) + (v1[2] * v1[2] + v1[3] * v1[3]);
;                     u32x4 w; w.x = cvt_pk_bf16(v0[0], v0[1]); w.y = cvt_pk_bf16(v0[2], v0[3]); w.z = cvt_pk_bf16(v1[0], v1[1]); w.w = cvt_pk_bf16(v1[2], v1[3]);
;                     *(u32x4*)(hb + off + bj * HALF) = w; }
	v_pk_add_f32 v[92:93], v[92:93], v[194:195]
	v_pk_add_f32 v[94:95], v[94:95], v[196:197]
	v_pk_add_f32 v[88:89], v[88:89], v[208:209]
	v_pk_add_f32 v[90:91], v[90:91], v[210:211]
	v_mul_f32_e32 v214, v92, v92
	v_fmac_f32_e32 v214, v93, v93
	v_fmac_f32_e32 v214, v94, v94
	v_fmac_f32_e32 v214, v95, v95
	v_fmac_f32_e32 v214, v88, v88
	v_fmac_f32_e32 v214, v89, v89
	v_fmac_f32_e32 v214, v90, v90
	v_fmac_f32_e32 v214, v91, v91
	v_cvt_pk_bf16_f32 v136, v92, v93
	v_cvt_pk_bf16_f32 v137, v94, v95
	v_cvt_pk_bf16_f32 v138, v88, v89
	v_cvt_pk_bf16_f32 v139, v90, v91
	global_store_dwordx4 v229, v[136:139], s[4:5]
	v_lshlrev_b32_e32 v194, 16, v140
	v_and_b32_e32 v195, 0xffff0000, v140
	v_lshlrev_b32_e32 v196, 16, v141
	v_and_b32_e32 v197, 0xffff0000, v141
	v_lshlrev_b32_e32 v208, 16, v142
	v_and_b32_e32 v209, 0xffff0000, v142
	v_lshlrev_b32_e32 v210, 16, v143
	v_and_b32_e32 v211, 0xffff0000, v143
	v_pk_add_f32 v[84:85], v[84:85], v[194:195]
	v_pk_add_f32 v[86:87], v[86:87], v[196:197]
	v_pk_add_f32 v[80:81], v[80:81], v[208:209]
	v_pk_add_f32 v[82:83], v[82:83], v[210:211]
	v_mul_f32_e32 v222, v84, v84
	v_fmac_f32_e32 v222, v85, v85
	v_fmac_f32_e32 v222, v86, v86
	v_fmac_f32_e32 v222, v87, v87
	v_fmac_f32_e32 v222, v80, v80
	v_fmac_f32_e32 v222, v81, v81
	v_fmac_f32_e32 v222, v82, v82
	v_fmac_f32_e32 v222, v83, v83
	v_cvt_pk_bf16_f32 v140, v84, v85
	v_cvt_pk_bf16_f32 v141, v86, v87
	v_cvt_pk_bf16_f32 v142, v80, v81
	v_cvt_pk_bf16_f32 v143, v82, v83
	global_store_dwordx4 v229, v[140:143], s[4:5] offset:256
	v_add_u32_e32 v229, 0x18000, v228
	v_lshlrev_b32_e32 v194, 16, v144
	v_and_b32_e32 v195, 0xffff0000, v144
	v_lshlrev_b32_e32 v196, 16, v145
	v_and_b32_e32 v197, 0xffff0000, v145
	v_lshlrev_b32_e32 v208, 16, v146
	v_and_b32_e32 v209, 0xffff0000, v146
	v_lshlrev_b32_e32 v210, 16, v147
	v_and_b32_e32 v211, 0xffff0000, v147
	v_pk_add_f32 v[76:77], v[76:77], v[194:195]
	v_pk_add_f32 v[78:79], v[78:79], v[196:197]
	v_pk_add_f32 v[72:73], v[72:73], v[208:209]
	v_pk_add_f32 v[74:75], v[74:75], v[210:211]
	v_mul_f32_e32 v215, v76, v76
	v_fmac_f32_e32 v215, v77, v77
	v_fmac_f32_e32 v215, v78, v78
	v_fmac_f32_e32 v215, v79, v79
	v_fmac_f32_e32 v215, v72, v72
	v_fmac_f32_e32 v215, v73, v73
	v_fmac_f32_e32 v215, v74, v74
	v_fmac_f32_e32 v215, v75, v75
	v_cvt_pk_bf16_f32 v144, v76, v77
	v_cvt_pk_bf16_f32 v145, v78, v79
	v_cvt_pk_bf16_f32 v146, v72, v73
	v_cvt_pk_bf16_f32 v147, v74, v75
	global_store_dwordx4 v229, v[144:147], s[4:5]
	v_lshlrev_b32_e32 v194, 16, v156
	v_and_b32_e32 v195, 0xffff0000, v156
	v_lshlrev_b32_e32 v196, 16, v157
	v_and_b32_e32 v197, 0xffff0000, v157
	v_lshlrev_b32_e32 v208, 16, v158
	v_and_b32_e32 v209, 0xffff0000, v158
	v_lshlrev_b32_e32 v210, 16, v159
	v_and_b32_e32 v211, 0xffff0000, v159
	v_pk_add_f32 v[68:69], v[68:69], v[194:195]
	v_pk_add_f32 v[70:71], v[70:71], v[196:197]
	v_pk_add_f32 v[64:65], v[64:65], v[208:209]
	v_pk_add_f32 v[66:67], v[66:67], v[210:211]
	v_mul_f32_e32 v223, v68, v68
	v_fmac_f32_e32 v223, v69, v69
	v_fmac_f32_e32 v223, v70, v70
	v_fmac_f32_e32 v223, v71, v71
	v_fmac_f32_e32 v223, v64, v64
	v_fmac_f32_e32 v223, v65, v65
	v_fmac_f32_e32 v223, v66, v66
	v_fmac_f32_e32 v223, v67, v67
	v_cvt_pk_bf16_f32 v156, v68, v69
	v_cvt_pk_bf16_f32 v157, v70, v71
	v_cvt_pk_bf16_f32 v158, v64, v65
	v_cvt_pk_bf16_f32 v159, v66, v67
	global_store_dwordx4 v229, v[156:159], s[4:5] offset:256
	v_add_u32_e32 v229, 0x40000, v228
	v_lshlrev_b32_e32 v194, 16, v160
	v_and_b32_e32 v195, 0xffff0000, v160
	v_lshlrev_b32_e32 v196, 16, v161
	v_and_b32_e32 v197, 0xffff0000, v161
	v_lshlrev_b32_e32 v208, 16, v162
	v_and_b32_e32 v209, 0xffff0000, v162
	v_lshlrev_b32_e32 v210, 16, v163
	v_and_b32_e32 v211, 0xffff0000, v163
	v_pk_add_f32 v[60:61], v[60:61], v[194:195]
	v_pk_add_f32 v[62:63], v[62:63], v[196:197]
	v_pk_add_f32 v[56:57], v[56:57], v[208:209]
	v_pk_add_f32 v[58:59], v[58:59], v[210:211]
	v_mul_f32_e32 v216, v60, v60
	v_fmac_f32_e32 v216, v61, v61
	v_fmac_f32_e32 v216, v62, v62
	v_fmac_f32_e32 v216, v63, v63
	v_fmac_f32_e32 v216, v56, v56
	v_fmac_f32_e32 v216, v57, v57
	v_fmac_f32_e32 v216, v58, v58
	v_fmac_f32_e32 v216, v59, v59
	v_cvt_pk_bf16_f32 v160, v60, v61
	v_cvt_pk_bf16_f32 v161, v62, v63
	v_cvt_pk_bf16_f32 v162, v56, v57
	v_cvt_pk_bf16_f32 v163, v58, v59
	global_store_dwordx4 v229, v[160:163], s[4:5]
	v_lshlrev_b32_e32 v194, 16, v164
	v_and_b32_e32 v195, 0xffff0000, v164
	v_lshlrev_b32_e32 v196, 16, v165
	v_and_b32_e32 v197, 0xffff0000, v165
	v_lshlrev_b32_e32 v208, 16, v166
	v_and_b32_e32 v209, 0xffff0000, v166
	v_lshlrev_b32_e32 v210, 16, v167
	v_and_b32_e32 v211, 0xffff0000, v167
	v_pk_add_f32 v[52:53], v[52:53], v[194:195]
	v_pk_add_f32 v[54:55], v[54:55], v[196:197]
	v_pk_add_f32 v[48:49], v[48:49], v[208:209]
	v_pk_add_f32 v[50:51], v[50:51], v[210:211]
	v_mul_f32_e32 v224, v52, v52
	v_fmac_f32_e32 v224, v53, v53
	v_fmac_f32_e32 v224, v54, v54
	v_fmac_f32_e32 v224, v55, v55
	v_fmac_f32_e32 v224, v48, v48
	v_fmac_f32_e32 v224, v49, v49
	v_fmac_f32_e32 v224, v50, v50
	v_fmac_f32_e32 v224, v51, v51
	v_cvt_pk_bf16_f32 v164, v52, v53
	v_cvt_pk_bf16_f32 v165, v54, v55
	v_cvt_pk_bf16_f32 v166, v48, v49
	v_cvt_pk_bf16_f32 v167, v50, v51
	global_store_dwordx4 v229, v[164:167], s[4:5] offset:256
	v_add_u32_e32 v229, 0x48000, v228
	v_lshlrev_b32_e32 v194, 16, v168
	v_and_b32_e32 v195, 0xffff0000, v168
	v_lshlrev_b32_e32 v196, 16, v169
	v_and_b32_e32 v197, 0xffff0000, v169
	v_lshlrev_b32_e32 v208, 16, v170
	v_and_b32_e32 v209, 0xffff0000, v170
	v_lshlrev_b32_e32 v210, 16, v171
	v_and_b32_e32 v211, 0xffff0000, v171
	v_pk_add_f32 v[44:45], v[44:45], v[194:195]
	v_pk_add_f32 v[46:47], v[46:47], v[196:197]
	v_pk_add_f32 v[40:41], v[40:41], v[208:209]
; __device__ __forceinline__ unsigned cvt_pk_bf16(float lo, float hi) { unsigned r; asm volatile("v_cvt_pk_bf16_f32 %0, %1, %2" : "=v"(r) : "v"(lo), "v"(hi)); return r; }
;     __device__ __forceinline__ void operator()(const f32x4 (&acc)[2][2][4][2], const Unit& u, int wr, int wc, int fr, int fq) const {
;     ...
;             for (int m = 0; m < 4; ++m) { const int row = row0 + ai * HALF + m * 16; const size_t off = (size_t)row * 1024 + col0; float ss = 0.f;
; #pragma unroll
;                 for (int bj = 0; bj < 2; ++bj) {
;                     const u32x4 b = bw[ai][m][bj];
;                     const f32x4 b0 = (f32x4){__uint_as_float(b.x << 16), __uint_as_float(b.x & 0xffff0000u), __uint_as_float(b.y << 16), __uint_as_float(b.y & 0xffff0000u)};
;                     const f32x4 b1 = (f32x4){__uint_as_float(b.z << 16), __uint_as_float(b.z & 0xffff0000u), __uint_as_float(b.w << 16), __uint_as_float(b.w & 0xffff0000u)};
;                     const f32x4 v0 = acc[ai][bj][m][0] + b0, v1 = acc[ai][bj][m][1] + b1;
;                     ss += (v0[0] * v0[0] + v0[1] * v0[1]) + (v0[2] * v0[2] + v0[3] * v0[3]) + (v1[0] * v1[0] + v1[1] * v1[1]) + (v1[2] * v1[2] + v1[3] * v1[3]);
;                     u32x4 w; w.x = cvt_pk_bf16(v0[0], v0[1]); w.y = cvt_pk_bf16(v0[2], v0[3]); w.z = cvt_pk_bf16(v1[0], v1[1]); w.w = cvt_pk_bf16(v1[2], v1[3]);
;                     *(u32x4*)(hb + off + bj * HALF) = w; }
;                 ss += __shfl_xor(ss, 16); ss += __shfl_xor(ss, 32);
;                 if (fq == 0) slots[(size_t)row * 16 + u.pn * 4 + wc] = ss; }
	v_pk_add_f32 v[42:43], v[42:43], v[210:211]
	v_mul_f32_e32 v217, v44, v44
	v_fmac_f32_e32 v217, v45, v45
	v_fmac_f32_e32 v217, v46, v46
	v_fmac_f32_e32 v217, v47, v47
	v_fmac_f32_e32 v217, v40, v40
	v_fmac_f32_e32 v217, v41, v41
	v_fmac_f32_e32 v217, v42, v42
	v_fmac_f32_e32 v217, v43, v43
	v_cvt_pk_bf16_f32 v168, v44, v45
	v_cvt_pk_bf16_f32 v169, v46, v47
	v_cvt_pk_bf16_f32 v170, v40, v41
	v_cvt_pk_bf16_f32 v171, v42, v43
	global_store_dwordx4 v229, v[168:171], s[4:5]
	v_lshlrev_b32_e32 v194, 16, v172
	v_and_b32_e32 v195, 0xffff0000, v172
	v_lshlrev_b32_e32 v196, 16, v173
	v_and_b32_e32 v197, 0xffff0000, v173
	v_lshlrev_b32_e32 v208, 16, v174
	v_and_b32_e32 v209, 0xffff0000, v174
	v_lshlrev_b32_e32 v210, 16, v175
	v_and_b32_e32 v211, 0xffff0000, v175
	v_pk_add_f32 v[36:37], v[36:37], v[194:195]
	v_pk_add_f32 v[38:39], v[38:39], v[196:197]
	v_pk_add_f32 v[32:33], v[32:33], v[208:209]
	v_pk_add_f32 v[34:35], v[34:35], v[210:211]
	v_mul_f32_e32 v225, v36, v36
	v_fmac_f32_e32 v225, v37, v37
	v_fmac_f32_e32 v225, v38, v38
	v_fmac_f32_e32 v225, v39, v39
	v_fmac_f32_e32 v225, v32, v32
	v_fmac_f32_e32 v225, v33, v33
	v_fmac_f32_e32 v225, v34, v34
	v_fmac_f32_e32 v225, v35, v35
	v_cvt_pk_bf16_f32 v172, v36, v37
	v_cvt_pk_bf16_f32 v173, v38, v39
	v_cvt_pk_bf16_f32 v174, v32, v33
	v_cvt_pk_bf16_f32 v175, v34, v35
	global_store_dwordx4 v229, v[172:175], s[4:5] offset:256
	v_add_u32_e32 v229, 0x50000, v228
	v_lshlrev_b32_e32 v194, 16, v176
	v_and_b32_e32 v195, 0xffff0000, v176
	v_lshlrev_b32_e32 v196, 16, v177
	v_and_b32_e32 v197, 0xffff0000, v177
	v_lshlrev_b32_e32 v208, 16, v178
	v_and_b32_e32 v209, 0xffff0000, v178
	v_lshlrev_b32_e32 v210, 16, v179
	v_and_b32_e32 v211, 0xffff0000, v179
	v_pk_add_f32 v[28:29], v[28:29], v[194:195]
	v_pk_add_f32 v[30:31], v[30:31], v[196:197]
	v_pk_add_f32 v[24:25], v[24:25], v[208:209]
	v_pk_add_f32 v[26:27], v[26:27], v[210:211]
	v_mul_f32_e32 v218, v28, v28
	v_fmac_f32_e32 v218, v29, v29
	v_fmac_f32_e32 v218, v30, v30
	v_fmac_f32_e32 v218, v31, v31
	v_fmac_f32_e32 v218, v24, v24
	v_fmac_f32_e32 v218, v25, v25
	v_fmac_f32_e32 v218, v26, v26
	v_fmac_f32_e32 v218, v27, v27
	v_cvt_pk_bf16_f32 v176, v28, v29
	v_cvt_pk_bf16_f32 v177, v30, v31
	v_cvt_pk_bf16_f32 v178, v24, v25
	v_cvt_pk_bf16_f32 v179, v26, v27
	global_store_dwordx4 v229, v[176:179], s[4:5]
	v_lshlrev_b32_e32 v194, 16, v180
	v_and_b32_e32 v195, 0xffff0000, v180
	v_lshlrev_b32_e32 v196, 16, v181
	v_and_b32_e32 v197, 0xffff0000, v181
	v_lshlrev_b32_e32 v208, 16, v182
	v_and_b32_e32 v209, 0xffff0000, v182
	v_lshlrev_b32_e32 v210, 16, v183
	v_and_b32_e32 v211, 0xffff0000, v183
	v_pk_add_f32 v[20:21], v[20:21], v[194:195]
	v_pk_add_f32 v[22:23], v[22:23], v[196:197]
	v_pk_add_f32 v[16:17], v[16:17], v[208:209]
	v_pk_add_f32 v[18:19], v[18:19], v[210:211]
	v_mul_f32_e32 v226, v20, v20
	v_fmac_f32_e32 v226, v21, v21
	v_fmac_f32_e32 v226, v22, v22
	v_fmac_f32_e32 v226, v23, v23
	v_fmac_f32_e32 v226, v16, v16
	v_fmac_f32_e32 v226, v17, v17
	v_fmac_f32_e32 v226, v18, v18
	v_fmac_f32_e32 v226, v19, v19
	v_cvt_pk_bf16_f32 v180, v20, v21
	v_cvt_pk_bf16_f32 v181, v22, v23
	v_cvt_pk_bf16_f32 v182, v16, v17
	v_cvt_pk_bf16_f32 v183, v18, v19
	global_store_dwordx4 v229, v[180:183], s[4:5] offset:256
	v_add_u32_e32 v229, 0x58000, v228
	v_lshlrev_b32_e32 v194, 16, v184
	v_and_b32_e32 v195, 0xffff0000, v184
	v_lshlrev_b32_e32 v196, 16, v185
	v_and_b32_e32 v197, 0xffff0000, v185
	v_lshlrev_b32_e32 v208, 16, v186
	v_and_b32_e32 v209, 0xffff0000, v186
	v_lshlrev_b32_e32 v210, 16, v187
	v_and_b32_e32 v211, 0xffff0000, v187
	v_pk_add_f32 v[12:13], v[12:13], v[194:195]
	v_pk_add_f32 v[14:15], v[14:15], v[196:197]
	v_pk_add_f32 v[8:9], v[8:9], v[208:209]
	v_pk_add_f32 v[10:11], v[10:11], v[210:211]
	v_mul_f32_e32 v219, v12, v12
	v_fmac_f32_e32 v219, v13, v13
	v_fmac_f32_e32 v219, v14, v14
	v_fmac_f32_e32 v219, v15, v15
	v_fmac_f32_e32 v219, v8, v8
	v_fmac_f32_e32 v219, v9, v9
	v_fmac_f32_e32 v219, v10, v10
	v_fmac_f32_e32 v219, v11, v11
	v_cvt_pk_bf16_f32 v184, v12, v13
	v_cvt_pk_bf16_f32 v185, v14, v15
	v_cvt_pk_bf16_f32 v186, v8, v9
	v_cvt_pk_bf16_f32 v187, v10, v11
	global_store_dwordx4 v229, v[184:187], s[4:5]
	v_lshlrev_b32_e32 v194, 16, v188
	v_and_b32_e32 v195, 0xffff0000, v188
	v_lshlrev_b32_e32 v196, 16, v189
	v_and_b32_e32 v197, 0xffff0000, v189
	v_lshlrev_b32_e32 v208, 16, v190
	v_and_b32_e32 v209, 0xffff0000, v190
	v_lshlrev_b32_e32 v210, 16, v191
	v_and_b32_e32 v211, 0xffff0000, v191
	v_pk_add_f32 v[4:5], v[4:5], v[194:195]
	v_pk_add_f32 v[6:7], v[6:7], v[196:197]
	v_pk_add_f32 v[0:1], v[0:1], v[208:209]
	v_pk_add_f32 v[2:3], v[2:3], v[210:211]
	v_mul_f32_e32 v227, v4, v4
	v_fmac_f32_e32 v227, v5, v5
	v_fmac_f32_e32 v227, v6, v6
	v_fmac_f32_e32 v227, v7, v7
	v_fmac_f32_e32 v227, v0, v0
	v_fmac_f32_e32 v227, v1, v1
	v_fmac_f32_e32 v227, v2, v2
	v_fmac_f32_e32 v227, v3, v3
	v_cvt_pk_bf16_f32 v188, v4, v5
	v_cvt_pk_bf16_f32 v189, v6, v7
	v_cvt_pk_bf16_f32 v190, v0, v1
	v_cvt_pk_bf16_f32 v191, v2, v3
	global_store_dwordx4 v229, v[188:191], s[4:5] offset:256
	v_add_f32_e32 v212, v212, v220
	v_add_f32_e32 v213, v213, v221
	v_add_f32_e32 v214, v214, v222
	v_add_f32_e32 v215, v215, v223
	v_add_f32_e32 v216, v216, v224
	v_add_f32_e32 v217, v217, v225
	v_add_f32_e32 v218, v218, v226
	v_add_f32_e32 v219, v219, v227
	ds_bpermute_b32 v232, v230, v212
	ds_bpermute_b32 v233, v230, v213
	ds_bpermute_b32 v234, v230, v214
	ds_bpermute_b32 v235, v230, v215
	ds_bpermute_b32 v236, v230, v216
	ds_bpermute_b32 v237, v230, v217
	ds_bpermute_b32 v238, v230, v218
	ds_bpermute_b32 v239, v230, v219
	s_waitcnt lgkmcnt(0)
	v_add_f32_e32 v212, v212, v232
	v_add_f32_e32 v213, v213, v233
	v_add_f32_e32 v214, v214, v234
	v_add_f32_e32 v215, v215, v235
	v_add_f32_e32 v216, v216, v236
	v_add_f32_e32 v217, v217, v237
	v_add_f32_e32 v218, v218, v238
	v_add_f32_e32 v219, v219, v239
	ds_bpermute_b32 v232, v231, v212
	ds_bpermute_b32 v233, v231, v213
	ds_bpermute_b32 v234, v231, v214
	ds_bpermute_b32 v235, v231, v215
	ds_bpermute_b32 v236, v231, v216
	ds_bpermute_b32 v237, v231, v217
	ds_bpermute_b32 v238, v231, v218
	ds_bpermute_b32 v239, v231, v219
	s_waitcnt lgkmcnt(0)
	v_add_f32_e32 v212, v212, v232
	v_add_f32_e32 v213, v213, v233
	v_add_f32_e32 v214, v214, v234
	v_add_f32_e32 v215, v215, v235
	v_add_f32_e32 v216, v216, v236
	v_add_f32_e32 v217, v217, v237
	v_add_f32_e32 v218, v218, v238
	v_add_f32_e32 v219, v219, v239
	s_and_saveexec_b64 s[24:25], s[40:41]
	global_store_dword v240, v212, s[10:11]
	global_store_dword v240, v213, s[10:11] offset:1024
	global_store_dword v240, v214, s[10:11] offset:2048
	global_store_dword v240, v215, s[10:11] offset:3072
	global_store_dword v241, v216, s[10:11]
	global_store_dword v241, v217, s[10:11] offset:1024
	global_store_dword v241, v218, s[10:11] offset:2048
	global_store_dword v241, v219, s[10:11] offset:3072
	s_or_b64 exec, exec, s[24:25]
	s_and_b64 vcc, exec, s[42:43]
	s_mov_b64 s[22:23], -1
	s_cbranch_vccnz .LBB0_580
	s_andn2_b64 vcc, exec, s[0:1]
	s_cbranch_vccnz .LBB0_579
	s_barrier
	s_branch .LBB0_579

; __device__ __forceinline__ unsigned cvt_pk_bf16(float lo, float hi) { unsigned r; asm volatile("v_cvt_pk_bf16_f32 %0, %1, %2" : "=v"(r) : "v"(lo), "v"(hi)); return r; }
;     __device__ __forceinline__ void operator()(const f32x4 (&acc)[2][2][4][2], const Unit& u, int wr, int wc, int fr, int fq) const {
;         const int row0 = u.pm * BM + wr * 64 + fr, col0 = u.pn * BM + wc * 32 + 8 * fq;
;         u32x4 bw[2][4][2];
; #pragma unroll
;         for (int ai = 0; ai < 2; ++ai)
; #pragma unroll
;             for (int m = 0; m < 4; ++m)
; #pragma unroll
;                 for (int bj = 0; bj < 2; ++bj) bw[ai][m][bj] = *(const u32x4*)(hb + (size_t)(row0 + ai * HALF + m * 16) * 1024 + col0 + bj * HALF);
; #pragma unroll
;         for (int ai = 0; ai < 2; ++ai) {
; #pragma unroll
;             for (int m = 0; m < 4; ++m) { const int row = row0 + ai * HALF + m * 16; const size_t off = (size_t)row * 1024 + col0; float ss = 0.f;
; #pragma unroll
;                 for (int bj = 0; bj < 2; ++bj) {
;                     const u32x4 b = bw[ai][m][bj];
;                     const f32x4 b0 = (f32x4){__uint_as_float(b.x << 16), __uint_as_float(b.x & 0xffff0000u), __uint_as_float(b.y << 16), __uint_as_float(b.y & 0xffff0000u)};
;                     const f32x4 b1 = (f32x4){__uint_as_float(b.z << 16), __uint_as_float(b.z & 0xffff0000u), __uint_as_float(b.w << 16), __uint_as_float(b.w & 0xffff0000u)};
;                     const f32x4 v0 = acc[ai][bj][m][0] + b0, v1 = acc[ai][bj][m][1] + b1;
;                     ss += (v0[0] * v0[0] + v0[1] * v0[1]) + (v0[2] * v0[2] + v0[3] * v0[3]) + (v1[0] * v1[0] + v1[1] * v1[1]) + (v1[2] * v1[2] + v1[3] * v1[3]);
;                     u32x4 w; w.x = cvt_pk_bf16(v0[0], v0[1]); w.y = cvt_pk_bf16(v0[2], v0[3]); w.z = cvt_pk_bf16(v1[0], v1[1]); w.w = cvt_pk_bf16(v1[2], v1[3]);
;                     *(u32x4*)(hb + off + bj * HALF) = w; }
;                 ss += __shfl_xor(ss, 16); ss += __shfl_xor(ss, 32);
;                 if (fq == 0) slots[(size_t)row * 16 + u.pn * 4 + wc] = ss; }
;             asm volatile("" ::: "memory");
;         }
;     }
.LBB0_1034:
	v_lshl_add_u32 v228, s71, 8, v248
	v_lshl_or_b32 v229, s6, 8, v250
	s_lshl_b32 s20, s6, 4
	s_lshl_b32 s86, s61, 2
	v_lshlrev_b32_e32 v240, 6, v228
	v_lshlrev_b32_e32 v228, 11, v228
	s_add_i32 s20, s20, s86
	v_lshl_add_u32 v228, v229, 1, v228
	v_add_u32_e32 v240, s20, v240
	global_load_dwordx4 v[112:115], v228, s[4:5]
	global_load_dwordx4 v[120:123], v228, s[4:5] offset:256
	v_add_u32_e32 v229, 0x8000, v228
	global_load_dwordx4 v[124:127], v229, s[4:5]
	global_load_dwordx4 v[128:131], v229, s[4:5] offset:256
	v_add_u32_e32 v229, 0x10000, v228
	global_load_dwordx4 v[136:139], v229, s[4:5]
	global_load_dwordx4 v[140:143], v229, s[4:5] offset:256
	v_add_u32_e32 v229, 0x18000, v228
	global_load_dwordx4 v[144:147], v229, s[4:5]
	global_load_dwordx4 v[156:159], v229, s[4:5] offset:256
	v_add_u32_e32 v229, 0x40000, v228
	global_load_dwordx4 v[160:163], v229, s[4:5]
	global_load_dwordx4 v[164:167], v229, s[4:5] offset:256
	v_add_u32_e32 v229, 0x48000, v228
	global_load_dwordx4 v[168:171], v229, s[4:5]
	global_load_dwordx4 v[172:175], v229, s[4:5] offset:256
	v_add_u32_e32 v229, 0x50000, v228
	global_load_dwordx4 v[176:179], v229, s[4:5]
	global_load_dwordx4 v[180:183], v229, s[4:5] offset:256
	v_add_u32_e32 v229, 0x58000, v228
	global_load_dwordx4 v[184:187], v229, s[4:5]
	global_load_dwordx4 v[188:191], v229, s[4:5] offset:256
	v_xor_b32_e32 v230, 16, v252
	v_xor_b32_e32 v231, 32, v252
	v_add_u32_e32 v241, 0x2000, v240
	v_lshlrev_b32_e32 v230, 2, v230
	v_lshlrev_b32_e32 v231, 2, v231
	s_waitcnt vmcnt(0)
	v_lshlrev_b32_e32 v194, 16, v112
	v_and_b32_e32 v195, 0xffff0000, v112
	v_lshlrev_b32_e32 v196, 16, v113
	v_and_b32_e32 v197, 0xffff0000, v113
	v_lshlrev_b32_e32 v208, 16, v114
	v_and_b32_e32 v209, 0xffff0000, v114
	v_lshlrev_b32_e32 v210, 16, v115
	v_and_b32_e32 v211, 0xffff0000, v115
	v_pk_add_f32 v[152:153], v[152:153], v[194:195]
	v_pk_add_f32 v[154:155], v[154:155], v[196:197]
	v_pk_add_f32 v[148:149], v[148:149], v[208:209]
	v_pk_add_f32 v[150:151], v[150:151], v[210:211]
	v_mul_f32_e32 v212, v152, v152
	v_fmac_f32_e32 v212, v153, v153
	v_fmac_f32_e32 v212, v154, v154
	v_fmac_f32_e32 v212, v155, v155
	v_fmac_f32_e32 v212, v148, v148
	v_fmac_f32_e32 v212, v149, v149
	v_fmac_f32_e32 v212, v150, v150
	v_fmac_f32_e32 v212, v151, v151
	v_cvt_pk_bf16_f32 v112, v152, v153
	v_cvt_pk_bf16_f32 v113, v154, v155
	v_cvt_pk_bf16_f32 v114, v148, v149
	v_cvt_pk_bf16_f32 v115, v150, v151
	global_store_dwordx4 v228, v[112:115], s[4:5]
	v_lshlrev_b32_e32 v194, 16, v120
	v_and_b32_e32 v195, 0xffff0000, v120
	v_lshlrev_b32_e32 v196, 16, v121
	v_and_b32_e32 v197, 0xffff0000, v121
	v_lshlrev_b32_e32 v208, 16, v122
	v_and_b32_e32 v209, 0xffff0000, v122
	v_lshlrev_b32_e32 v210, 16, v123
	v_and_b32_e32 v211, 0xffff0000, v123
	v_pk_add_f32 v[132:133], v[132:133], v[194:195]
	v_pk_add_f32 v[134:135], v[134:135], v[196:197]
	v_pk_add_f32 v[116:117], v[116:117], v[208:209]
	v_pk_add_f32 v[118:119], v[118:119], v[210:211]
	v_mul_f32_e32 v220, v132, v132
	v_fmac_f32_e32 v220, v133, v133
	v_fmac_f32_e32 v220, v134, v134
	v_fmac_f32_e32 v220, v135, v135
	v_fmac_f32_e32 v220, v116, v116
	v_fmac_f32_e32 v220, v117, v117
	v_fmac_f32_e32 v220, v118, v118
	v_fmac_f32_e32 v220, v119, v119
	v_cvt_pk_bf16_f32 v120, v132, v133
	v_cvt_pk_bf16_f32 v121, v134, v135
	v_cvt_pk_bf16_f32 v122, v116, v117
	v_cvt_pk_bf16_f32 v123, v118, v119
	global_store_dwordx4 v228, v[120:123], s[4:5] offset:256
	v_add_u32_e32 v229, 0x8000, v228
	v_lshlrev_b32_e32 v194, 16, v124
	v_and_b32_e32 v195, 0xffff0000, v124
	v_lshlrev_b32_e32 v196, 16, v125
	v_and_b32_e32 v197, 0xffff0000, v125
	v_lshlrev_b32_e32 v208, 16, v126
	v_and_b32_e32 v209, 0xffff0000, v126
	v_lshlrev_b32_e32 v210, 16, v127
	v_and_b32_e32 v211, 0xffff0000, v127
	v_pk_add_f32 v[108:109], v[108:109], v[194:195]
	v_pk_add_f32 v[110:111], v[110:111], v[196:197]
	v_pk_add_f32 v[104:105], v[104:105], v[208:209]
	v_pk_add_f32 v[106:107], v[106:107], v[210:211]
	v_mul_f32_e32 v213, v108, v108
	v_fmac_f32_e32 v213, v109, v109
	v_fmac_f32_e32 v213, v110, v110
	v_fmac_f32_e32 v213, v111, v111
	v_fmac_f32_e32 v213, v104, v104
	v_fmac_f32_e32 v213, v105, v105
	v_fmac_f32_e32 v213, v106, v106
	v_fmac_f32_e32 v213, v107, v107
	v_cvt_pk_bf16_f32 v124, v108, v109
	v_cvt_pk_bf16_f32 v125, v110, v111
	v_cvt_pk_bf16_f32 v126, v104, v105
	v_cvt_pk_bf16_f32 v127, v106, v107
	global_store_dwordx4 v229, v[124:127], s[4:5]
	v_lshlrev_b32_e32 v194, 16, v128
	v_and_b32_e32 v195, 0xffff0000, v128
	v_lshlrev_b32_e32 v196, 16, v129
	v_and_b32_e32 v197, 0xffff0000, v129
	v_lshlrev_b32_e32 v208, 16, v130
	v_and_b32_e32 v209, 0xffff0000, v130
	v_lshlrev_b32_e32 v210, 16, v131
	v_and_b32_e32 v211, 0xffff0000, v131
	v_pk_add_f32 v[100:101], v[100:101], v[194:195]
	v_pk_add_f32 v[102:103], v[102:103], v[196:197]
	v_pk_add_f32 v[96:97], v[96:97], v[208:209]
	v_pk_add_f32 v[98:99], v[98:99], v[210:211]
	v_mul_f32_e32 v221, v100, v100
	v_fmac_f32_e32 v221, v101, v101
	v_fmac_f32_e32 v221, v102, v102
	v_fmac_f32_e32 v221, v103, v103
	v_fmac_f32_e32 v221, v96, v96
	v_fmac_f32_e32 v221, v97, v97
	v_fmac_f32_e32 v221, v98, v98
	v_fmac_f32_e32 v221, v99, v99
	v_cvt_pk_bf16_f32 v128, v100, v101
	v_cvt_pk_bf16_f32 v129, v102, v103
	v_cvt_pk_bf16_f32 v130, v96, v97
	v_cvt_pk_bf16_f32 v131, v98, v99
	global_store_dwordx4 v229, v[128:131], s[4:5] offset:256
	v_add_u32_e32 v229, 0x10000, v228
	v_lshlrev_b32_e32 v194, 16, v136
	v_and_b32_e32 v195, 0xffff0000, v136
	v_lshlrev_b32_e32 v196, 16, v137
	v_and_b32_e32 v197, 0xffff0000, v137
	v_lshlrev_b32_e32 v208, 16, v138
	v_and_b32_e32 v209, 0xffff0000, v138
	v_lshlrev_b32_e32 v210, 16, v139
	v_and_b32_e32 v211, 0xffff0000, v139
; __device__ __forceinline__ unsigned cvt_pk_bf16(float lo, float hi) { unsigned r; asm volatile("v_cvt_pk_bf16_f32 %0, %1, %2" : "=v"(r) : "v"(lo), "v"(hi)); return r; }
;     __device__ __forceinline__ void operator()(const f32x4 (&acc)[2][2][4][2], const Unit& u, int wr, int wc, int fr, int fq) const {
;     ...
;             for (int m = 0; m < 4; ++m) { const int row = row0 + ai * HALF + m * 16; const size_t off = (size_t)row * 1024 + col0; float ss = 0.f;
; #pragma unroll
;                 for (int bj = 0; bj < 2; ++bj) {
;                     const u32x4 b = bw[ai][m][bj];
;                     const f32x4 b0 = (f32x4){__uint_as_float(b.x << 16), __uint_as_float(b.x & 0xffff0000u), __uint_as_float(b.y << 16), __uint_as_float(b.y & 0xffff0000u)};
;                     const f32x4 b1 = (f32x4){__uint_as_float(b.z << 16), __uint_as_float(b.z & 0xffff0000u), __uint_as_float(b.w << 16), __uint_as_float(b.w & 0xffff0000u)};
;                     const f32x4 v0 = acc[ai][bj][m][0] + b0, v1 = acc[ai][bj][m][1] + b1;
;                     ss += (v0[0] * v0[0] + v0[1] * v0[1]) + (v0[2] * v0[2] + v0[3] * v0[3]) + (v1[0] * v1[0] + v1[1] * v1[1]) + (v1[2] * v1[2] + v1[3] * v1[3]);
;                     u32x4 w; w.x = cvt_pk_bf16(v0[0], v0[1]); w.y = cvt_pk_bf16(v0[2], v0[3]); w.z = cvt_pk_bf16(v1[0], v1[1]); w.w = cvt_pk_bf16(v1[2], v1[3]);
;                     *(u32x4*)(hb + off + bj * HALF) = w; }
	v_pk_add_f32 v[92:93], v[92:93], v[194:195]
	v_pk_add_f32 v[94:95], v[94:95], v[196:197]
	v_pk_add_f32 v[88:89], v[88:89], v[208:209]
	v_pk_add_f32 v[90:91], v[90:91], v[210:211]
	v_mul_f32_e32 v214, v92, v92
	v_fmac_f32_e32 v214, v93, v93
	v_fmac_f32_e32 v214, v94, v94
	v_fmac_f32_e32 v214, v95, v95
	v_fmac_f32_e32 v214, v88, v88
	v_fmac_f32_e32 v214, v89, v89
	v_fmac_f32_e32 v214, v90, v90
	v_fmac_f32_e32 v214, v91, v91
	v_cvt_pk_bf16_f32 v136, v92, v93
	v_cvt_pk_bf16_f32 v137, v94, v95
	v_cvt_pk_bf16_f32 v138, v88, v89
	v_cvt_pk_bf16_f32 v139, v90, v91
	global_store_dwordx4 v229, v[136:139], s[4:5]
	v_lshlrev_b32_e32 v194, 16, v140
	v_and_b32_e32 v195, 0xffff0000, v140
	v_lshlrev_b32_e32 v196, 16, v141
	v_and_b32_e32 v197, 0xffff0000, v141
	v_lshlrev_b32_e32 v208, 16, v142
	v_and_b32_e32 v209, 0xffff0000, v142
	v_lshlrev_b32_e32 v210, 16, v143
	v_and_b32_e32 v211, 0xffff0000, v143
	v_pk_add_f32 v[84:85], v[84:85], v[194:195]
	v_pk_add_f32 v[86:87], v[86:87], v[196:197]
	v_pk_add_f32 v[80:81], v[80:81], v[208:209]
	v_pk_add_f32 v[82:83], v[82:83], v[210:211]
	v_mul_f32_e32 v222, v84, v84
	v_fmac_f32_e32 v222, v85, v85
	v_fmac_f32_e32 v222, v86, v86
	v_fmac_f32_e32 v222, v87, v87
	v_fmac_f32_e32 v222, v80, v80
	v_fmac_f32_e32 v222, v81, v81
	v_fmac_f32_e32 v222, v82, v82
	v_fmac_f32_e32 v222, v83, v83
	v_cvt_pk_bf16_f32 v140, v84, v85
	v_cvt_pk_bf16_f32 v141, v86, v87
	v_cvt_pk_bf16_f32 v142, v80, v81
	v_cvt_pk_bf16_f32 v143, v82, v83
	global_store_dwordx4 v229, v[140:143], s[4:5] offset:256
	v_add_u32_e32 v229, 0x18000, v228
	v_lshlrev_b32_e32 v194, 16, v144
	v_and_b32_e32 v195, 0xffff0000, v144
	v_lshlrev_b32_e32 v196, 16, v145
	v_and_b32_e32 v197, 0xffff0000, v145
	v_lshlrev_b32_e32 v208, 16, v146
	v_and_b32_e32 v209, 0xffff0000, v146
	v_lshlrev_b32_e32 v210, 16, v147
	v_and_b32_e32 v211, 0xffff0000, v147
	v_pk_add_f32 v[76:77], v[76:77], v[194:195]
	v_pk_add_f32 v[78:79], v[78:79], v[196:197]
	v_pk_add_f32 v[72:73], v[72:73], v[208:209]
	v_pk_add_f32 v[74:75], v[74:75], v[210:211]
	v_mul_f32_e32 v215, v76, v76
	v_fmac_f32_e32 v215, v77, v77
	v_fmac_f32_e32 v215, v78, v78
	v_fmac_f32_e32 v215, v79, v79
	v_fmac_f32_e32 v215, v72, v72
	v_fmac_f32_e32 v215, v73, v73
	v_fmac_f32_e32 v215, v74, v74
	v_fmac_f32_e32 v215, v75, v75
	v_cvt_pk_bf16_f32 v144, v76, v77
	v_cvt_pk_bf16_f32 v145, v78, v79
	v_cvt_pk_bf16_f32 v146, v72, v73
	v_cvt_pk_bf16_f32 v147, v74, v75
	global_store_dwordx4 v229, v[144:147], s[4:5]
	v_lshlrev_b32_e32 v194, 16, v156
	v_and_b32_e32 v195, 0xffff0000, v156
	v_lshlrev_b32_e32 v196, 16, v157
	v_and_b32_e32 v197, 0xffff0000, v157
	v_lshlrev_b32_e32 v208, 16, v158
	v_and_b32_e32 v209, 0xffff0000, v158
	v_lshlrev_b32_e32 v210, 16, v159
	v_and_b32_e32 v211, 0xffff0000, v159
	v_pk_add_f32 v[68:69], v[68:69], v[194:195]
	v_pk_add_f32 v[70:71], v[70:71], v[196:197]
	v_pk_add_f32 v[64:65], v[64:65], v[208:209]
	v_pk_add_f32 v[66:67], v[66:67], v[210:211]
	v_mul_f32_e32 v223, v68, v68
	v_fmac_f32_e32 v223, v69, v69
	v_fmac_f32_e32 v223, v70, v70
	v_fmac_f32_e32 v223, v71, v71
	v_fmac_f32_e32 v223, v64, v64
	v_fmac_f32_e32 v223, v65, v65
	v_fmac_f32_e32 v223, v66, v66
	v_fmac_f32_e32 v223, v67, v67
	v_cvt_pk_bf16_f32 v156, v68, v69
	v_cvt_pk_bf16_f32 v157, v70, v71
	v_cvt_pk_bf16_f32 v158, v64, v65
	v_cvt_pk_bf16_f32 v159, v66, v67
	global_store_dwordx4 v229, v[156:159], s[4:5] offset:256
	v_add_u32_e32 v229, 0x40000, v228
	v_lshlrev_b32_e32 v194, 16, v160
	v_and_b32_e32 v195, 0xffff0000, v160
	v_lshlrev_b32_e32 v196, 16, v161
	v_and_b32_e32 v197, 0xffff0000, v161
	v_lshlrev_b32_e32 v208, 16, v162
	v_and_b32_e32 v209, 0xffff0000, v162
	v_lshlrev_b32_e32 v210, 16, v163
	v_and_b32_e32 v211, 0xffff0000, v163
	v_pk_add_f32 v[60:61], v[60:61], v[194:195]
	v_pk_add_f32 v[62:63], v[62:63], v[196:197]
	v_pk_add_f32 v[56:57], v[56:57], v[208:209]
	v_pk_add_f32 v[58:59], v[58:59], v[210:211]
	v_mul_f32_e32 v216, v60, v60
	v_fmac_f32_e32 v216, v61, v61
	v_fmac_f32_e32 v216, v62, v62
	v_fmac_f32_e32 v216, v63, v63
	v_fmac_f32_e32 v216, v56, v56
	v_fmac_f32_e32 v216, v57, v57
	v_fmac_f32_e32 v216, v58, v58
	v_fmac_f32_e32 v216, v59, v59
	v_cvt_pk_bf16_f32 v160, v60, v61
	v_cvt_pk_bf16_f32 v161, v62, v63
	v_cvt_pk_bf16_f32 v162, v56, v57
	v_cvt_pk_bf16_f32 v163, v58, v59
	global_store_dwordx4 v229, v[160:163], s[4:5]
	v_lshlrev_b32_e32 v194, 16, v164
	v_and_b32_e32 v195, 0xffff0000, v164
	v_lshlrev_b32_e32 v196, 16, v165
	v_and_b32_e32 v197, 0xffff0000, v165
	v_lshlrev_b32_e32 v208, 16, v166
	v_and_b32_e32 v209, 0xffff0000, v166
	v_lshlrev_b32_e32 v210, 16, v167
	v_and_b32_e32 v211, 0xffff0000, v167
	v_pk_add_f32 v[52:53], v[52:53], v[194:195]
	v_pk_add_f32 v[54:55], v[54:55], v[196:197]
	v_pk_add_f32 v[48:49], v[48:49], v[208:209]
	v_pk_add_f32 v[50:51], v[50:51], v[210:211]
	v_mul_f32_e32 v224, v52, v52
	v_fmac_f32_e32 v224, v53, v53
	v_fmac_f32_e32 v224, v54, v54
	v_fmac_f32_e32 v224, v55, v55
	v_fmac_f32_e32 v224, v48, v48
	v_fmac_f32_e32 v224, v49, v49
	v_fmac_f32_e32 v224, v50, v50
	v_fmac_f32_e32 v224, v51, v51
	v_cvt_pk_bf16_f32 v164, v52, v53
	v_cvt_pk_bf16_f32 v165, v54, v55
	v_cvt_pk_bf16_f32 v166, v48, v49
	v_cvt_pk_bf16_f32 v167, v50, v51
	global_store_dwordx4 v229, v[164:167], s[4:5] offset:256
	v_add_u32_e32 v229, 0x48000, v228
	v_lshlrev_b32_e32 v194, 16, v168
	v_and_b32_e32 v195, 0xffff0000, v168
	v_lshlrev_b32_e32 v196, 16, v169
	v_and_b32_e32 v197, 0xffff0000, v169
	v_lshlrev_b32_e32 v208, 16, v170
	v_and_b32_e32 v209, 0xffff0000, v170
	v_lshlrev_b32_e32 v210, 16, v171
	v_and_b32_e32 v211, 0xffff0000, v171
	v_pk_add_f32 v[44:45], v[44:45], v[194:195]
	v_pk_add_f32 v[46:47], v[46:47], v[196:197]
	v_pk_add_f32 v[40:41], v[40:41], v[208:209]
; __device__ __forceinline__ unsigned cvt_pk_bf16(float lo, float hi) { unsigned r; asm volatile("v_cvt_pk_bf16_f32 %0, %1, %2" : "=v"(r) : "v"(lo), "v"(hi)); return r; }
;     __device__ __forceinline__ void operator()(const f32x4 (&acc)[2][2][4][2], const Unit& u, int wr, int wc, int fr, int fq) const {
;     ...
;             for (int m = 0; m < 4; ++m) { const int row = row0 + ai * HALF + m * 16; const size_t off = (size_t)row * 1024 + col0; float ss = 0.f;
; #pragma unroll
;                 for (int bj = 0; bj < 2; ++bj) {
;                     const u32x4 b = bw[ai][m][bj];
;                     const f32x4 b0 = (f32x4){__uint_as_float(b.x << 16), __uint_as_float(b.x & 0xffff0000u), __uint_as_float(b.y << 16), __uint_as_float(b.y & 0xffff0000u)};
;                     const f32x4 b1 = (f32x4){__uint_as_float(b.z << 16), __uint_as_float(b.z & 0xffff0000u), __uint_as_float(b.w << 16), __uint_as_float(b.w & 0xffff0000u)};
;                     const f32x4 v0 = acc[ai][bj][m][0] + b0, v1 = acc[ai][bj][m][1] + b1;
;                     ss += (v0[0] * v0[0] + v0[1] * v0[1]) + (v0[2] * v0[2] + v0[3] * v0[3]) + (v1[0] * v1[0] + v1[1] * v1[1]) + (v1[2] * v1[2] + v1[3] * v1[3]);
;                     u32x4 w; w.x = cvt_pk_bf16(v0[0], v0[1]); w.y = cvt_pk_bf16(v0[2], v0[3]); w.z = cvt_pk_bf16(v1[0], v1[1]); w.w = cvt_pk_bf16(v1[2], v1[3]);
;                     *(u32x4*)(hb + off + bj * HALF) = w; }
;                 ss += __shfl_xor(ss, 16); ss += __shfl_xor(ss, 32);
;                 if (fq == 0) slots[(size_t)row * 16 + u.pn * 4 + wc] = ss; }
	v_pk_add_f32 v[42:43], v[42:43], v[210:211]
	v_mul_f32_e32 v217, v44, v44
	v_fmac_f32_e32 v217, v45, v45
	v_fmac_f32_e32 v217, v46, v46
	v_fmac_f32_e32 v217, v47, v47
	v_fmac_f32_e32 v217, v40, v40
	v_fmac_f32_e32 v217, v41, v41
	v_fmac_f32_e32 v217, v42, v42
	v_fmac_f32_e32 v217, v43, v43
	v_cvt_pk_bf16_f32 v168, v44, v45
	v_cvt_pk_bf16_f32 v169, v46, v47
	v_cvt_pk_bf16_f32 v170, v40, v41
	v_cvt_pk_bf16_f32 v171, v42, v43
	global_store_dwordx4 v229, v[168:171], s[4:5]
	v_lshlrev_b32_e32 v194, 16, v172
	v_and_b32_e32 v195, 0xffff0000, v172
	v_lshlrev_b32_e32 v196, 16, v173
	v_and_b32_e32 v197, 0xffff0000, v173
	v_lshlrev_b32_e32 v208, 16, v174
	v_and_b32_e32 v209, 0xffff0000, v174
	v_lshlrev_b32_e32 v210, 16, v175
	v_and_b32_e32 v211, 0xffff0000, v175
	v_pk_add_f32 v[36:37], v[36:37], v[194:195]
	v_pk_add_f32 v[38:39], v[38:39], v[196:197]
	v_pk_add_f32 v[32:33], v[32:33], v[208:209]
	v_pk_add_f32 v[34:35], v[34:35], v[210:211]
	v_mul_f32_e32 v225, v36, v36
	v_fmac_f32_e32 v225, v37, v37
	v_fmac_f32_e32 v225, v38, v38
	v_fmac_f32_e32 v225, v39, v39
	v_fmac_f32_e32 v225, v32, v32
	v_fmac_f32_e32 v225, v33, v33
	v_fmac_f32_e32 v225, v34, v34
	v_fmac_f32_e32 v225, v35, v35
	v_cvt_pk_bf16_f32 v172, v36, v37
	v_cvt_pk_bf16_f32 v173, v38, v39
	v_cvt_pk_bf16_f32 v174, v32, v33
	v_cvt_pk_bf16_f32 v175, v34, v35
	global_store_dwordx4 v229, v[172:175], s[4:5] offset:256
	v_add_u32_e32 v229, 0x50000, v228
	v_lshlrev_b32_e32 v194, 16, v176
	v_and_b32_e32 v195, 0xffff0000, v176
	v_lshlrev_b32_e32 v196, 16, v177
	v_and_b32_e32 v197, 0xffff0000, v177
	v_lshlrev_b32_e32 v208, 16, v178
	v_and_b32_e32 v209, 0xffff0000, v178
	v_lshlrev_b32_e32 v210, 16, v179
	v_and_b32_e32 v211, 0xffff0000, v179
	v_pk_add_f32 v[28:29], v[28:29], v[194:195]
	v_pk_add_f32 v[30:31], v[30:31], v[196:197]
	v_pk_add_f32 v[24:25], v[24:25], v[208:209]
	v_pk_add_f32 v[26:27], v[26:27], v[210:211]
	v_mul_f32_e32 v218, v28, v28
	v_fmac_f32_e32 v218, v29, v29
	v_fmac_f32_e32 v218, v30, v30
	v_fmac_f32_e32 v218, v31, v31
	v_fmac_f32_e32 v218, v24, v24
	v_fmac_f32_e32 v218, v25, v25
	v_fmac_f32_e32 v218, v26, v26
	v_fmac_f32_e32 v218, v27, v27
	v_cvt_pk_bf16_f32 v176, v28, v29
	v_cvt_pk_bf16_f32 v177, v30, v31
	v_cvt_pk_bf16_f32 v178, v24, v25
	v_cvt_pk_bf16_f32 v179, v26, v27
	global_store_dwordx4 v229, v[176:179], s[4:5]
	v_lshlrev_b32_e32 v194, 16, v180
	v_and_b32_e32 v195, 0xffff0000, v180
	v_lshlrev_b32_e32 v196, 16, v181
	v_and_b32_e32 v197, 0xffff0000, v181
	v_lshlrev_b32_e32 v208, 16, v182
	v_and_b32_e32 v209, 0xffff0000, v182
	v_lshlrev_b32_e32 v210, 16, v183
	v_and_b32_e32 v211, 0xffff0000, v183
	v_pk_add_f32 v[20:21], v[20:21], v[194:195]
	v_pk_add_f32 v[22:23], v[22:23], v[196:197]
	v_pk_add_f32 v[16:17], v[16:17], v[208:209]
	v_pk_add_f32 v[18:19], v[18:19], v[210:211]
	v_mul_f32_e32 v226, v20, v20
	v_fmac_f32_e32 v226, v21, v21
	v_fmac_f32_e32 v226, v22, v22
	v_fmac_f32_e32 v226, v23, v23
	v_fmac_f32_e32 v226, v16, v16
	v_fmac_f32_e32 v226, v17, v17
	v_fmac_f32_e32 v226, v18, v18
	v_fmac_f32_e32 v226, v19, v19
	v_cvt_pk_bf16_f32 v180, v20, v21
	v_cvt_pk_bf16_f32 v181, v22, v23
	v_cvt_pk_bf16_f32 v182, v16, v17
	v_cvt_pk_bf16_f32 v183, v18, v19
	global_store_dwordx4 v229, v[180:183], s[4:5] offset:256
	v_add_u32_e32 v229, 0x58000, v228
	v_lshlrev_b32_e32 v194, 16, v184
	v_and_b32_e32 v195, 0xffff0000, v184
	v_lshlrev_b32_e32 v196, 16, v185
	v_and_b32_e32 v197, 0xffff0000, v185
	v_lshlrev_b32_e32 v208, 16, v186
	v_and_b32_e32 v209, 0xffff0000, v186
	v_lshlrev_b32_e32 v210, 16, v187
	v_and_b32_e32 v211, 0xffff0000, v187
	v_pk_add_f32 v[12:13], v[12:13], v[194:195]
	v_pk_add_f32 v[14:15], v[14:15], v[196:197]
	v_pk_add_f32 v[8:9], v[8:9], v[208:209]
	v_pk_add_f32 v[10:11], v[10:11], v[210:211]
	v_mul_f32_e32 v219, v12, v12
	v_fmac_f32_e32 v219, v13, v13
	v_fmac_f32_e32 v219, v14, v14
	v_fmac_f32_e32 v219, v15, v15
	v_fmac_f32_e32 v219, v8, v8
	v_fmac_f32_e32 v219, v9, v9
	v_fmac_f32_e32 v219, v10, v10
	v_fmac_f32_e32 v219, v11, v11
	v_cvt_pk_bf16_f32 v184, v12, v13
	v_cvt_pk_bf16_f32 v185, v14, v15
	v_cvt_pk_bf16_f32 v186, v8, v9
	v_cvt_pk_bf16_f32 v187, v10, v11
	global_store_dwordx4 v229, v[184:187], s[4:5]
	v_lshlrev_b32_e32 v194, 16, v188
	v_and_b32_e32 v195, 0xffff0000, v188
	v_lshlrev_b32_e32 v196, 16, v189
	v_and_b32_e32 v197, 0xffff0000, v189
	v_lshlrev_b32_e32 v208, 16, v190
	v_and_b32_e32 v209, 0xffff0000, v190
	v_lshlrev_b32_e32 v210, 16, v191
	v_and_b32_e32 v211, 0xffff0000, v191
	v_pk_add_f32 v[4:5], v[4:5], v[194:195]
	v_pk_add_f32 v[6:7], v[6:7], v[196:197]
	v_pk_add_f32 v[0:1], v[0:1], v[208:209]
	v_pk_add_f32 v[2:3], v[2:3], v[210:211]
	v_mul_f32_e32 v227, v4, v4
	v_fmac_f32_e32 v227, v5, v5
	v_fmac_f32_e32 v227, v6, v6
	v_fmac_f32_e32 v227, v7, v7
	v_fmac_f32_e32 v227, v0, v0
	v_fmac_f32_e32 v227, v1, v1
	v_fmac_f32_e32 v227, v2, v2
	v_fmac_f32_e32 v227, v3, v3
	v_cvt_pk_bf16_f32 v188, v4, v5
	v_cvt_pk_bf16_f32 v189, v6, v7
	v_cvt_pk_bf16_f32 v190, v0, v1
	v_cvt_pk_bf16_f32 v191, v2, v3
	global_store_dwordx4 v229, v[188:191], s[4:5] offset:256
	v_add_f32_e32 v212, v212, v220
	v_add_f32_e32 v213, v213, v221
	v_add_f32_e32 v214, v214, v222
	v_add_f32_e32 v215, v215, v223
	v_add_f32_e32 v216, v216, v224
	v_add_f32_e32 v217, v217, v225
	v_add_f32_e32 v218, v218, v226
	v_add_f32_e32 v219, v219, v227
	ds_bpermute_b32 v232, v230, v212
	ds_bpermute_b32 v233, v230, v213
	ds_bpermute_b32 v234, v230, v214
	ds_bpermute_b32 v235, v230, v215
	ds_bpermute_b32 v236, v230, v216
	ds_bpermute_b32 v237, v230, v217
	ds_bpermute_b32 v238, v230, v218
	ds_bpermute_b32 v239, v230, v219
	s_waitcnt lgkmcnt(0)
	v_add_f32_e32 v212, v212, v232
	v_add_f32_e32 v213, v213, v233
	v_add_f32_e32 v214, v214, v234
	v_add_f32_e32 v215, v215, v235
	v_add_f32_e32 v216, v216, v236
	v_add_f32_e32 v217, v217, v237
	v_add_f32_e32 v218, v218, v238
	v_add_f32_e32 v219, v219, v239
	ds_bpermute_b32 v232, v231, v212
	ds_bpermute_b32 v233, v231, v213
	ds_bpermute_b32 v234, v231, v214
	ds_bpermute_b32 v235, v231, v215
	ds_bpermute_b32 v236, v231, v216
	ds_bpermute_b32 v237, v231, v217
	ds_bpermute_b32 v238, v231, v218
	ds_bpermute_b32 v239, v231, v219
	s_waitcnt lgkmcnt(0)
	v_add_f32_e32 v212, v212, v232
	v_add_f32_e32 v213, v213, v233
	v_add_f32_e32 v214, v214, v234
	v_add_f32_e32 v215, v215, v235
	v_add_f32_e32 v216, v216, v236
	v_add_f32_e32 v217, v217, v237
	v_add_f32_e32 v218, v218, v238
	v_add_f32_e32 v219, v219, v239
	s_and_saveexec_b64 s[20:21], s[38:39]
	global_store_dword v240, v212, s[8:9]
	global_store_dword v240, v213, s[8:9] offset:1024
	global_store_dword v240, v214, s[8:9] offset:2048
	global_store_dword v240, v215, s[8:9] offset:3072
	global_store_dword v241, v216, s[8:9]
	global_store_dword v241, v217, s[8:9] offset:1024
	global_store_dword v241, v218, s[8:9] offset:2048
	global_store_dword v241, v219, s[8:9] offset:3072
	s_or_b64 exec, exec, s[20:21]
	s_movk_i32 s29, 0x1600
	s_and_b64 vcc, exec, s[40:41]
	s_mov_b64 s[16:17], -1
	s_cbranch_vccnz .LBB0_1019
	s_andn2_b64 vcc, exec, s[0:1]
	s_cbranch_vccnz .LBB0_1018
	s_barrier
	s_branch .LBB0_1018
